# norm loops consolidated + residual tile L2/MALL touch at unit start in 6 EpiRes GEMMs
# baseline (speedup 1.0000x reference)
;     __device__ __forceinline__ void operator()(const f32x4 (&acc)[2][2][4][2], const Unit& u, int wr, int wc, int fr, int fq) const {
;     ...
;                     for (int bj = 0; bj < 2; ++bj) xw[m][bj] = *(const u32x4*)((const bf16_t*)xin + (size_t)(row0 + ai * HALF + m * 16) * 2048 + col0 + bj * HALF);
; template <class Epi, class Sched, bool ALIGN_EPI = true, bool SP2 = true, bool FULLLINE = false, bool NOSTAGE = false, bool FP8 = false>
; __device__ __forceinline__ void gemm_phase(PG8_LAS unsigned char* lds, const Gemm g, const Sched& S, const Epi& E) {
;     ...
;     for (;;) {
;         const bool has_next = S.next(ui + 1, nxt);
;         const char* nA = has_next ? PG8_ABASE(nxt) : cA; const char* nB = has_next ? PG8_BBASE(nxt) : cB;
.LBB0_865:
	s_lshl_b32 s100, s83, 20
	s_lshl_b32 s101, s84, 9
	s_add_u32 s100, s100, s101
	s_add_u32 s100, s60, s100
	s_addc_u32 s101, s61, 0
	v_lshrrev_b32_e32 v253, 2, v0
	v_and_b32_e32 v254, 3, v0
	v_lshlrev_b32_e32 v253, 12, v253
	v_lshl_or_b32 v253, v254, 7, v253
	s_nop 0
	global_load_dword v254, v253, s[100:101]
	s_add_u32 s100, s100, 0x80000
	s_addc_u32 s101, s101, 0
	s_nop 0
	global_load_dword v254, v253, s[100:101]
	s_nop 0
	v_cndmask_b32_e64 v2, 0, 1, s[10:11]
	v_cmp_ne_u32_e64 s[8:9], 1, v2
	s_andn2_b64 vcc, exec, s[10:11]
	s_mov_b64 s[10:11], s[70:71]
	s_cbranch_vccnz .LBB0_867
	s_mul_i32 s1, s82, 0x2c0000
	s_mul_hi_i32 s0, s82, 0x2c0000
	s_add_u32 s10, s96, s1
	s_addc_u32 s11, s97, s0

.LBB0_1207:
	s_lshl_b32 s100, s74, 20
	s_lshl_b32 s101, s75, 9
	s_add_u32 s100, s100, s101
	s_add_u32 s100, s60, s100
	s_addc_u32 s101, s61, 0
	v_lshrrev_b32_e32 v253, 2, v0
	v_and_b32_e32 v254, 3, v0
	v_lshlrev_b32_e32 v253, 12, v253
	v_lshl_or_b32 v253, v254, 7, v253
	s_nop 0
	global_load_dword v254, v253, s[100:101]
	s_add_u32 s100, s100, 0x80000
	s_addc_u32 s101, s101, 0
	s_nop 0
	global_load_dword v254, v253, s[100:101]
	s_ashr_i32 s69, s68, 31
	ds_read_b128 v[2:5], v1
	ds_read_b128 v[6:9], v1 offset:1024
	ds_read_b128 v[10:13], v1 offset:2048
	ds_read_b128 v[14:17], v1 offset:3072
	ds_read_b128 v[18:21], v192
	ds_read_b128 v[22:25], v192 offset:1024
	ds_read_b128 v[26:29], v192 offset:2048
	ds_read_b128 v[30:33], v192 offset:3072
	s_lshl_b64 s[0:1], s[68:69], 20
	s_add_u32 s70, s42, s0
	s_addc_u32 s71, s43, s1
	s_and_b64 s[0:1], s[8:9], exec
	s_cselect_b32 s69, s71, s77
	s_cselect_b32 s92, s70, s76
	s_ashr_i32 s67, s66, 31
	s_lshl_b64 s[0:1], s[66:67], 20
	s_add_u32 s72, s44, s0
	s_addc_u32 s73, s45, s1
	s_and_b64 s[0:1], s[8:9], exec
	s_cselect_b32 s67, s73, s79
	s_cselect_b32 s93, s72, s78
	v_lshl_add_u64 v[248:249], s[76:77], 0, v[170:171]
	s_mov_b32 m0, s88
	v_lshl_add_u64 v[66:67], v[248:249], 0, s[12:13]
	ds_read_b128 v[34:37], v193
	ds_read_b128 v[38:41], v193 offset:1024
	ds_read_b128 v[42:45], v193 offset:2048
	ds_read_b128 v[46:49], v193 offset:3072
	ds_read_b128 v[50:53], v193 offset:4096
	ds_read_b128 v[54:57], v193 offset:5120
	ds_read_b128 v[58:61], v193 offset:6144
	ds_read_b128 v[62:65], v193 offset:7168
	global_load_lds_dwordx4 v[66:67], off
	v_lshl_add_u64 v[66:67], v[248:249], 0, s[14:15]
	s_mov_b32 m0, s89
	s_nop 0
	global_load_lds_dwordx4 v[66:67], off
	s_waitcnt vmcnt(24)
	s_waitcnt lgkmcnt(0)
	s_barrier
	s_waitcnt lgkmcnt(0)
	v_mfma_f32_16x16x32_bf16 v[66:69], v[2:5], v[34:37], 0
	v_mfma_f32_16x16x32_bf16 v[70:73], v[10:13], v[34:37], 0
	v_mfma_f32_16x16x32_bf16 v[78:81], v[10:13], v[42:45], 0
	v_mfma_f32_16x16x32_bf16 v[86:89], v[10:13], v[50:53], 0
	v_mfma_f32_16x16x32_bf16 v[66:69], v[6:9], v[38:41], v[66:69]
	v_mfma_f32_16x16x32_bf16 v[70:73], v[14:17], v[38:41], v[70:73]
	v_mfma_f32_16x16x32_bf16 v[74:77], v[2:5], v[42:45], 0
	v_mfma_f32_16x16x32_bf16 v[78:81], v[14:17], v[46:49], v[78:81]
	v_mfma_f32_16x16x32_bf16 v[82:85], v[2:5], v[50:53], 0
	v_mfma_f32_16x16x32_bf16 v[86:89], v[14:17], v[54:57], v[86:89]
	v_mfma_f32_16x16x32_bf16 v[90:93], v[2:5], v[58:61], 0
	v_mfma_f32_16x16x32_bf16 v[94:97], v[10:13], v[58:61], 0
	v_mfma_f32_16x16x32_bf16 v[74:77], v[6:9], v[46:49], v[74:77]
	v_mfma_f32_16x16x32_bf16 v[82:85], v[6:9], v[54:57], v[82:85]
	v_mfma_f32_16x16x32_bf16 v[90:93], v[6:9], v[62:65], v[90:93]
	v_mfma_f32_16x16x32_bf16 v[94:97], v[14:17], v[62:65], v[94:97]
	v_mfma_f32_16x16x32_bf16 v[98:101], v[18:21], v[34:37], 0
	v_mfma_f32_16x16x32_bf16 v[34:37], v[26:29], v[34:37], 0
	v_mfma_f32_16x16x32_bf16 v[98:101], v[22:25], v[38:41], v[98:101]
	v_mfma_f32_16x16x32_bf16 v[34:37], v[30:33], v[38:41], v[34:37]
	v_mfma_f32_16x16x32_bf16 v[38:41], v[18:21], v[42:45], 0
	v_mfma_f32_16x16x32_bf16 v[42:45], v[26:29], v[42:45], 0
	v_mfma_f32_16x16x32_bf16 v[38:41], v[22:25], v[46:49], v[38:41]
	v_mfma_f32_16x16x32_bf16 v[42:45], v[30:33], v[46:49], v[42:45]
	v_mfma_f32_16x16x32_bf16 v[46:49], v[18:21], v[50:53], 0
	v_mfma_f32_16x16x32_bf16 v[50:53], v[26:29], v[50:53], 0
	v_mfma_f32_16x16x32_bf16 v[46:49], v[22:25], v[54:57], v[46:49]
	v_mfma_f32_16x16x32_bf16 v[50:53], v[30:33], v[54:57], v[50:53]
	v_mfma_f32_16x16x32_bf16 v[54:57], v[18:21], v[58:61], 0
	v_mfma_f32_16x16x32_bf16 v[58:61], v[26:29], v[58:61], 0
	v_mfma_f32_16x16x32_bf16 v[54:57], v[22:25], v[62:65], v[54:57]
	v_mfma_f32_16x16x32_bf16 v[58:61], v[30:33], v[62:65], v[58:61]
	s_barrier
	v_lshl_add_u64 v[250:251], s[78:79], 0, v[172:173]
	s_add_i32 s94, s85, s46
	v_lshl_add_u64 v[130:131], v[250:251], 0, s[16:17]
	s_mov_b32 m0, s94
	s_add_i32 s95, s94, 0x2000
	ds_read_b128 v[62:65], v193 offset:16384
	ds_read_b128 v[102:105], v193 offset:17408
	ds_read_b128 v[106:109], v193 offset:18432
	ds_read_b128 v[110:113], v193 offset:19456
	ds_read_b128 v[114:117], v193 offset:20480
	ds_read_b128 v[118:121], v193 offset:21504
	ds_read_b128 v[122:125], v193 offset:22528
	ds_read_b128 v[126:129], v193 offset:23552
	global_load_lds_dwordx4 v[130:131], off
	v_lshl_add_u64 v[130:131], v[250:251], 0, s[18:19]
	s_mov_b32 m0, s95
	s_add_i32 s40, s87, s46
	global_load_lds_dwordx4 v[130:131], off
	v_lshl_add_u64 v[130:131], v[250:251], 0, s[20:21]
	s_mov_b32 m0, s40
	s_add_i32 s41, s40, 0x2000
	global_load_lds_dwordx4 v[130:131], off
	v_lshl_add_u64 v[130:131], v[250:251], 0, s[22:23]
	s_mov_b32 m0, s41
	s_nop 0
	global_load_lds_dwordx4 v[130:131], off
	v_lshl_add_u64 v[130:131], v[248:249], 0, s[16:17]
	s_mov_b32 m0, s47
	s_nop 0
	global_load_lds_dwordx4 v[130:131], off
	v_lshl_add_u64 v[130:131], v[248:249], 0, s[18:19]
	s_mov_b32 m0, s52
	s_nop 0
	global_load_lds_dwordx4 v[130:131], off
	s_waitcnt vmcnt(24)
	s_waitcnt lgkmcnt(0)
	s_barrier
	s_waitcnt lgkmcnt(0)
	v_mfma_f32_16x16x32_bf16 v[130:133], v[2:5], v[62:65], 0
	v_mfma_f32_16x16x32_bf16 v[138:141], v[6:9], v[102:105], v[130:133]
	v_mfma_f32_16x16x32_bf16 v[130:133], v[10:13], v[62:65], 0
	v_mfma_f32_16x16x32_bf16 v[150:153], v[14:17], v[102:105], v[130:133]
	v_mfma_f32_16x16x32_bf16 v[130:133], v[2:5], v[106:109], 0
	v_mfma_f32_16x16x32_bf16 v[154:157], v[6:9], v[110:113], v[130:133]
	v_mfma_f32_16x16x32_bf16 v[130:133], v[10:13], v[106:109], 0
	v_mfma_f32_16x16x32_bf16 v[158:161], v[14:17], v[110:113], v[130:133]
	v_mfma_f32_16x16x32_bf16 v[130:133], v[2:5], v[114:117], 0
	v_mfma_f32_16x16x32_bf16 v[2:5], v[2:5], v[122:125], 0
	v_mfma_f32_16x16x32_bf16 v[162:165], v[6:9], v[118:121], v[130:133]
	v_mfma_f32_16x16x32_bf16 v[2:5], v[6:9], v[126:129], v[2:5]
	v_mfma_f32_16x16x32_bf16 v[6:9], v[10:13], v[122:125], 0
	v_mfma_f32_16x16x32_bf16 v[130:133], v[10:13], v[114:117], 0
	v_mfma_f32_16x16x32_bf16 v[6:9], v[14:17], v[126:129], v[6:9]
	v_mfma_f32_16x16x32_bf16 v[166:169], v[14:17], v[118:121], v[130:133]
	v_mfma_f32_16x16x32_bf16 v[10:13], v[18:21], v[62:65], 0
	v_mfma_f32_16x16x32_bf16 v[180:183], v[22:25], v[102:105], v[10:13]
	v_mfma_f32_16x16x32_bf16 v[10:13], v[26:29], v[62:65], 0
	v_mfma_f32_16x16x32_bf16 v[184:187], v[30:33], v[102:105], v[10:13]
	v_mfma_f32_16x16x32_bf16 v[10:13], v[18:21], v[106:109], 0
	v_mfma_f32_16x16x32_bf16 v[188:191], v[22:25], v[110:113], v[10:13]
	v_mfma_f32_16x16x32_bf16 v[10:13], v[26:29], v[106:109], 0
	v_mfma_f32_16x16x32_bf16 v[196:199], v[30:33], v[110:113], v[10:13]
	v_mfma_f32_16x16x32_bf16 v[10:13], v[18:21], v[114:117], 0
	v_mfma_f32_16x16x32_bf16 v[200:203], v[22:25], v[118:121], v[10:13]
	v_mfma_f32_16x16x32_bf16 v[10:13], v[26:29], v[114:117], 0
	v_mfma_f32_16x16x32_bf16 v[204:207], v[30:33], v[118:121], v[10:13]
	v_mfma_f32_16x16x32_bf16 v[10:13], v[18:21], v[122:125], 0
	v_mfma_f32_16x16x32_bf16 v[208:211], v[22:25], v[126:129], v[10:13]
	v_mfma_f32_16x16x32_bf16 v[10:13], v[26:29], v[122:125], 0
	v_mfma_f32_16x16x32_bf16 v[212:215], v[30:33], v[126:129], v[10:13]
	s_barrier
	s_nop 5
	ds_read_b128 v[10:13], v194
	ds_read_b128 v[14:17], v194 offset:1024
	ds_read_b128 v[18:21], v194 offset:2048
	ds_read_b128 v[22:25], v194 offset:3072
	ds_read_b128 v[216:219], v195
	ds_read_b128 v[220:223], v195 offset:1024
	ds_read_b128 v[224:227], v195 offset:2048
	ds_read_b128 v[228:231], v195 offset:3072
	s_mov_b32 m0, s53
	v_lshl_add_u64 v[106:107], v[248:249], 0, s[20:21]
	ds_read_b128 v[26:29], v193 offset:32768
	ds_read_b128 v[30:33], v193 offset:33792
	ds_read_b128 v[62:65], v193 offset:34816
	ds_read_b128 v[102:105], v193 offset:35840
	ds_read_b128 v[232:235], v193 offset:36864
	ds_read_b128 v[236:239], v193 offset:37888
	ds_read_b128 v[240:243], v193 offset:38912
	ds_read_b128 v[244:247], v193 offset:39936
	global_load_lds_dwordx4 v[106:107], off
	v_lshl_add_u64 v[106:107], v[248:249], 0, s[22:23]
	s_mov_b32 m0, s54
	s_nop 0
	global_load_lds_dwordx4 v[106:107], off
	s_waitcnt vmcnt(8)
	s_waitcnt lgkmcnt(0)
	s_barrier
	s_waitcnt lgkmcnt(0)
	v_mfma_f32_16x16x32_bf16 v[66:69], v[10:13], v[26:29], v[66:69]
	v_mfma_f32_16x16x32_bf16 v[146:149], v[14:17], v[30:33], v[66:69]
	v_mfma_f32_16x16x32_bf16 v[66:69], v[18:21], v[26:29], v[70:73]
	v_mfma_f32_16x16x32_bf16 v[142:145], v[22:25], v[30:33], v[66:69]
	v_mfma_f32_16x16x32_bf16 v[66:69], v[10:13], v[62:65], v[74:77]
	v_mfma_f32_16x16x32_bf16 v[126:129], v[14:17], v[102:105], v[66:69]
	v_mfma_f32_16x16x32_bf16 v[66:69], v[18:21], v[62:65], v[78:81]
	v_mfma_f32_16x16x32_bf16 v[122:125], v[22:25], v[102:105], v[66:69]
	v_mfma_f32_16x16x32_bf16 v[66:69], v[10:13], v[232:235], v[82:85]
	v_mfma_f32_16x16x32_bf16 v[110:113], v[14:17], v[236:239], v[66:69]
	v_mfma_f32_16x16x32_bf16 v[66:69], v[18:21], v[232:235], v[86:89]
	v_mfma_f32_16x16x32_bf16 v[106:109], v[22:25], v[236:239], v[66:69]
	v_mfma_f32_16x16x32_bf16 v[66:69], v[10:13], v[240:243], v[90:93]
	v_mfma_f32_16x16x32_bf16 v[86:89], v[14:17], v[244:247], v[66:69]
	v_mfma_f32_16x16x32_bf16 v[66:69], v[18:21], v[240:243], v[94:97]
	v_mfma_f32_16x16x32_bf16 v[78:81], v[22:25], v[244:247], v[66:69]
	v_mfma_f32_16x16x32_bf16 v[66:69], v[216:219], v[26:29], v[98:101]
	v_mfma_f32_16x16x32_bf16 v[26:29], v[224:227], v[26:29], v[34:37]
	v_mfma_f32_16x16x32_bf16 v[130:133], v[228:231], v[30:33], v[26:29]
	v_mfma_f32_16x16x32_bf16 v[26:29], v[216:219], v[62:65], v[38:41]
	v_mfma_f32_16x16x32_bf16 v[118:121], v[220:223], v[102:105], v[26:29]
	v_mfma_f32_16x16x32_bf16 v[26:29], v[224:227], v[62:65], v[42:45]
	v_mfma_f32_16x16x32_bf16 v[114:117], v[228:231], v[102:105], v[26:29]
	v_mfma_f32_16x16x32_bf16 v[26:29], v[216:219], v[232:235], v[46:49]
	v_mfma_f32_16x16x32_bf16 v[102:105], v[220:223], v[236:239], v[26:29]
	v_mfma_f32_16x16x32_bf16 v[26:29], v[224:227], v[232:235], v[50:53]
	v_mfma_f32_16x16x32_bf16 v[98:101], v[228:231], v[236:239], v[26:29]
	v_mfma_f32_16x16x32_bf16 v[26:29], v[216:219], v[240:243], v[54:57]
	v_mfma_f32_16x16x32_bf16 v[70:73], v[220:223], v[244:247], v[26:29]
	v_mfma_f32_16x16x32_bf16 v[26:29], v[224:227], v[240:243], v[58:61]
	v_mfma_f32_16x16x32_bf16 v[134:137], v[220:223], v[30:33], v[66:69]
	v_mfma_f32_16x16x32_bf16 v[66:69], v[228:231], v[244:247], v[26:29]
	s_barrier
; #define PG8_WAIT_V(n) asm volatile("s_waitcnt vmcnt(" #n ")" ::: "memory")
; template <class Epi, class Sched, bool ALIGN_EPI = true, bool SP2 = true, bool FULLLINE = false, bool NOSTAGE = false, bool FP8 = false>
; __device__ __forceinline__ void gemm_phase(PG8_LAS unsigned char* lds, const Gemm g, const Sched& S, const Epi& E) {
;     ...
;         for (int t = 2; t < nt; t += 2) PG8_ITER(PG8_WAIT_V(8));
	s_add_i32 s50, s90, s46
	s_nop 3
	v_lshl_add_u64 v[26:27], v[250:251], 0, s[24:25]
	s_mov_b32 m0, s50
	s_add_i32 s51, s50, 0x2000
	ds_read_b128 v[34:37], v193 offset:49152
	ds_read_b128 v[38:41], v193 offset:50176
	ds_read_b128 v[74:77], v193 offset:51200
	ds_read_b128 v[82:85], v193 offset:52224
	ds_read_b128 v[90:93], v193 offset:53248
	ds_read_b128 v[94:97], v193 offset:54272
	ds_read_b128 v[232:235], v193 offset:55296
	ds_read_b128 v[236:239], v193 offset:56320
	global_load_lds_dwordx4 v[26:27], off
	v_lshl_add_u64 v[26:27], v[250:251], 0, s[26:27]
	s_mov_b32 m0, s51
	s_mov_b64 s[0:1], 0x80180
	s_add_i32 s33, s91, s46
	global_load_lds_dwordx4 v[26:27], off
	v_lshl_add_u64 v[26:27], v[250:251], 0, s[0:1]
	s_mov_b32 m0, s33
	s_mov_b64 s[0:1], 0xc0180
	s_add_i32 s56, s33, 0x2000
	global_load_lds_dwordx4 v[26:27], off
	v_lshl_add_u64 v[26:27], v[250:251], 0, s[0:1]
	s_mov_b32 m0, s56
	s_nop 0
	global_load_lds_dwordx4 v[26:27], off
	v_lshl_add_u64 v[26:27], v[248:249], 0, s[24:25]
	s_mov_b32 m0, s55
	s_nop 0
	global_load_lds_dwordx4 v[26:27], off
	v_lshl_add_u64 v[26:27], v[248:249], 0, s[26:27]
	s_mov_b32 m0, s62
	s_nop 0
	global_load_lds_dwordx4 v[26:27], off
	s_waitcnt vmcnt(8)
	s_waitcnt lgkmcnt(0)
	s_barrier
	s_waitcnt lgkmcnt(0)
	v_mfma_f32_16x16x32_bf16 v[26:29], v[10:13], v[34:37], v[138:141]
	v_mfma_f32_16x16x32_bf16 v[62:65], v[14:17], v[38:41], v[26:29]
	v_mfma_f32_16x16x32_bf16 v[26:29], v[18:21], v[34:37], v[150:153]
	v_mfma_f32_16x16x32_bf16 v[58:61], v[22:25], v[38:41], v[26:29]
	v_mfma_f32_16x16x32_bf16 v[26:29], v[10:13], v[74:77], v[154:157]
	v_mfma_f32_16x16x32_bf16 v[46:49], v[14:17], v[82:85], v[26:29]
	v_mfma_f32_16x16x32_bf16 v[26:29], v[18:21], v[74:77], v[158:161]
	v_mfma_f32_16x16x32_bf16 v[42:45], v[22:25], v[82:85], v[26:29]
	v_mfma_f32_16x16x32_bf16 v[26:29], v[10:13], v[90:93], v[162:165]
	v_mfma_f32_16x16x32_bf16 v[2:5], v[10:13], v[232:235], v[2:5]
	v_mfma_f32_16x16x32_bf16 v[30:33], v[14:17], v[94:97], v[26:29]
	v_mfma_f32_16x16x32_bf16 v[26:29], v[18:21], v[90:93], v[166:169]
	v_mfma_f32_16x16x32_bf16 v[14:17], v[14:17], v[236:239], v[2:5]
	v_mfma_f32_16x16x32_bf16 v[2:5], v[18:21], v[232:235], v[6:9]
	v_mfma_f32_16x16x32_bf16 v[26:29], v[22:25], v[94:97], v[26:29]
	v_mfma_f32_16x16x32_bf16 v[10:13], v[22:25], v[236:239], v[2:5]
	v_mfma_f32_16x16x32_bf16 v[2:5], v[216:219], v[34:37], v[180:183]
	v_mfma_f32_16x16x32_bf16 v[54:57], v[220:223], v[38:41], v[2:5]
	v_mfma_f32_16x16x32_bf16 v[2:5], v[224:227], v[34:37], v[184:187]
	v_mfma_f32_16x16x32_bf16 v[50:53], v[228:231], v[38:41], v[2:5]
	v_mfma_f32_16x16x32_bf16 v[2:5], v[216:219], v[74:77], v[188:191]
	v_mfma_f32_16x16x32_bf16 v[38:41], v[220:223], v[82:85], v[2:5]
	v_mfma_f32_16x16x32_bf16 v[2:5], v[224:227], v[74:77], v[196:199]
	v_mfma_f32_16x16x32_bf16 v[34:37], v[228:231], v[82:85], v[2:5]
	v_mfma_f32_16x16x32_bf16 v[2:5], v[216:219], v[90:93], v[200:203]
	v_mfma_f32_16x16x32_bf16 v[22:25], v[220:223], v[94:97], v[2:5]
	v_mfma_f32_16x16x32_bf16 v[2:5], v[224:227], v[90:93], v[204:207]
	v_mfma_f32_16x16x32_bf16 v[18:21], v[228:231], v[94:97], v[2:5]
	v_mfma_f32_16x16x32_bf16 v[2:5], v[216:219], v[232:235], v[208:211]
	v_mfma_f32_16x16x32_bf16 v[6:9], v[220:223], v[236:239], v[2:5]
	v_mfma_f32_16x16x32_bf16 v[2:5], v[224:227], v[232:235], v[212:215]
	v_mfma_f32_16x16x32_bf16 v[2:5], v[228:231], v[236:239], v[2:5]
	s_barrier
	s_add_u32 s76, s76, 0x80180
	s_addc_u32 s77, s77, 0
	s_add_u32 s57, s78, 0x200
	s_addc_u32 s78, s79, 0
	s_mov_b32 s79, 0

.LBB0_2096:
	s_lshl_b32 s100, s72, 20
	s_lshl_b32 s101, s73, 9
	s_add_u32 s100, s100, s101
	s_add_u32 s100, s60, s100
	s_addc_u32 s101, s61, 0
	v_lshrrev_b32_e32 v253, 2, v0
	v_and_b32_e32 v254, 3, v0
	v_lshlrev_b32_e32 v253, 12, v253
	v_lshl_or_b32 v253, v254, 7, v253
	s_nop 0
	global_load_dword v254, v253, s[100:101]
	s_add_u32 s100, s100, 0x80000
	s_addc_u32 s101, s101, 0
	s_nop 0
	global_load_dword v254, v253, s[100:101]
	s_ashr_i32 s67, s66, 31
	ds_read_b128 v[2:5], v1
	ds_read_b128 v[6:9], v1 offset:1024
	ds_read_b128 v[10:13], v1 offset:2048
	ds_read_b128 v[14:17], v1 offset:3072
	ds_read_b128 v[18:21], v192
	ds_read_b128 v[22:25], v192 offset:1024
	ds_read_b128 v[26:29], v192 offset:2048
	ds_read_b128 v[30:33], v192 offset:3072
	s_lshl_b64 s[0:1], s[66:67], 20
	s_add_u32 s68, s42, s0
	s_addc_u32 s69, s43, s1
	s_and_b64 s[0:1], s[8:9], exec
	s_cselect_b32 s67, s69, s75
	s_cselect_b32 s90, s68, s74
	s_ashr_i32 s41, s40, 31
	s_lshl_b64 s[0:1], s[40:41], 20
	s_add_u32 s70, s44, s0
	s_addc_u32 s71, s45, s1
	s_and_b64 s[0:1], s[8:9], exec
	s_cselect_b32 s41, s71, s77
	s_cselect_b32 s91, s70, s76
	v_lshl_add_u64 v[248:249], s[74:75], 0, v[170:171]
	s_mov_b32 m0, s85
	v_lshl_add_u64 v[66:67], v[248:249], 0, s[12:13]
	ds_read_b128 v[34:37], v193
	ds_read_b128 v[38:41], v193 offset:1024
	ds_read_b128 v[42:45], v193 offset:2048
	ds_read_b128 v[46:49], v193 offset:3072
	ds_read_b128 v[50:53], v193 offset:4096
	ds_read_b128 v[54:57], v193 offset:5120
	ds_read_b128 v[58:61], v193 offset:6144
	ds_read_b128 v[62:65], v193 offset:7168
	global_load_lds_dwordx4 v[66:67], off
	v_lshl_add_u64 v[66:67], v[248:249], 0, s[14:15]
	s_mov_b32 m0, s87
	s_nop 0
	global_load_lds_dwordx4 v[66:67], off
	s_waitcnt vmcnt(24)
	s_waitcnt lgkmcnt(0)
	s_barrier
	s_waitcnt lgkmcnt(0)
	v_mfma_f32_16x16x32_bf16 v[66:69], v[2:5], v[34:37], 0
	v_mfma_f32_16x16x32_bf16 v[70:73], v[10:13], v[34:37], 0
	v_mfma_f32_16x16x32_bf16 v[78:81], v[10:13], v[42:45], 0
	v_mfma_f32_16x16x32_bf16 v[86:89], v[10:13], v[50:53], 0
	v_mfma_f32_16x16x32_bf16 v[66:69], v[6:9], v[38:41], v[66:69]
	v_mfma_f32_16x16x32_bf16 v[70:73], v[14:17], v[38:41], v[70:73]
	v_mfma_f32_16x16x32_bf16 v[74:77], v[2:5], v[42:45], 0
	v_mfma_f32_16x16x32_bf16 v[78:81], v[14:17], v[46:49], v[78:81]
	v_mfma_f32_16x16x32_bf16 v[82:85], v[2:5], v[50:53], 0
	v_mfma_f32_16x16x32_bf16 v[86:89], v[14:17], v[54:57], v[86:89]
	v_mfma_f32_16x16x32_bf16 v[90:93], v[2:5], v[58:61], 0
	v_mfma_f32_16x16x32_bf16 v[94:97], v[10:13], v[58:61], 0
	v_mfma_f32_16x16x32_bf16 v[74:77], v[6:9], v[46:49], v[74:77]
	v_mfma_f32_16x16x32_bf16 v[82:85], v[6:9], v[54:57], v[82:85]
	v_mfma_f32_16x16x32_bf16 v[90:93], v[6:9], v[62:65], v[90:93]
	v_mfma_f32_16x16x32_bf16 v[94:97], v[14:17], v[62:65], v[94:97]
	v_mfma_f32_16x16x32_bf16 v[98:101], v[18:21], v[34:37], 0
	v_mfma_f32_16x16x32_bf16 v[34:37], v[26:29], v[34:37], 0
	v_mfma_f32_16x16x32_bf16 v[98:101], v[22:25], v[38:41], v[98:101]
	v_mfma_f32_16x16x32_bf16 v[34:37], v[30:33], v[38:41], v[34:37]
	v_mfma_f32_16x16x32_bf16 v[38:41], v[18:21], v[42:45], 0
	v_mfma_f32_16x16x32_bf16 v[42:45], v[26:29], v[42:45], 0
	v_mfma_f32_16x16x32_bf16 v[38:41], v[22:25], v[46:49], v[38:41]
	v_mfma_f32_16x16x32_bf16 v[42:45], v[30:33], v[46:49], v[42:45]
	v_mfma_f32_16x16x32_bf16 v[46:49], v[18:21], v[50:53], 0
	v_mfma_f32_16x16x32_bf16 v[50:53], v[26:29], v[50:53], 0
	v_mfma_f32_16x16x32_bf16 v[46:49], v[22:25], v[54:57], v[46:49]
	v_mfma_f32_16x16x32_bf16 v[50:53], v[30:33], v[54:57], v[50:53]
	v_mfma_f32_16x16x32_bf16 v[54:57], v[18:21], v[58:61], 0
	v_mfma_f32_16x16x32_bf16 v[58:61], v[26:29], v[58:61], 0
	v_mfma_f32_16x16x32_bf16 v[54:57], v[22:25], v[62:65], v[54:57]
	v_mfma_f32_16x16x32_bf16 v[58:61], v[30:33], v[62:65], v[58:61]
	s_barrier
	v_lshl_add_u64 v[250:251], s[76:77], 0, v[172:173]
	s_add_i32 s92, s83, s46
	v_lshl_add_u64 v[130:131], v[250:251], 0, s[16:17]
	s_mov_b32 m0, s92
	s_add_i32 s93, s92, 0x2000
	ds_read_b128 v[62:65], v193 offset:16384
	ds_read_b128 v[102:105], v193 offset:17408
	ds_read_b128 v[106:109], v193 offset:18432
	ds_read_b128 v[110:113], v193 offset:19456
	ds_read_b128 v[114:117], v193 offset:20480
	ds_read_b128 v[118:121], v193 offset:21504
	ds_read_b128 v[122:125], v193 offset:22528
	ds_read_b128 v[126:129], v193 offset:23552
	global_load_lds_dwordx4 v[130:131], off
	v_lshl_add_u64 v[130:131], v[250:251], 0, s[18:19]
	s_mov_b32 m0, s93
	s_add_i32 s94, s84, s46
	global_load_lds_dwordx4 v[130:131], off
	v_lshl_add_u64 v[130:131], v[250:251], 0, s[20:21]
	s_mov_b32 m0, s94
	s_add_i32 s95, s94, 0x2000
	global_load_lds_dwordx4 v[130:131], off
	v_lshl_add_u64 v[130:131], v[250:251], 0, s[22:23]
	s_mov_b32 m0, s95
	s_nop 0
	global_load_lds_dwordx4 v[130:131], off
	v_lshl_add_u64 v[130:131], v[248:249], 0, s[16:17]
	s_mov_b32 m0, s47
	s_nop 0
	global_load_lds_dwordx4 v[130:131], off
	v_lshl_add_u64 v[130:131], v[248:249], 0, s[18:19]
	s_mov_b32 m0, s52
	s_nop 0
	global_load_lds_dwordx4 v[130:131], off
	s_waitcnt vmcnt(24)
	s_waitcnt lgkmcnt(0)
	s_barrier
	s_waitcnt lgkmcnt(0)
	v_mfma_f32_16x16x32_bf16 v[130:133], v[2:5], v[62:65], 0
	v_mfma_f32_16x16x32_bf16 v[138:141], v[6:9], v[102:105], v[130:133]
	v_mfma_f32_16x16x32_bf16 v[130:133], v[10:13], v[62:65], 0
	v_mfma_f32_16x16x32_bf16 v[150:153], v[14:17], v[102:105], v[130:133]
	v_mfma_f32_16x16x32_bf16 v[130:133], v[2:5], v[106:109], 0
	v_mfma_f32_16x16x32_bf16 v[154:157], v[6:9], v[110:113], v[130:133]
	v_mfma_f32_16x16x32_bf16 v[130:133], v[10:13], v[106:109], 0
	v_mfma_f32_16x16x32_bf16 v[158:161], v[14:17], v[110:113], v[130:133]
	v_mfma_f32_16x16x32_bf16 v[130:133], v[2:5], v[114:117], 0
	v_mfma_f32_16x16x32_bf16 v[2:5], v[2:5], v[122:125], 0
	v_mfma_f32_16x16x32_bf16 v[162:165], v[6:9], v[118:121], v[130:133]
	v_mfma_f32_16x16x32_bf16 v[2:5], v[6:9], v[126:129], v[2:5]
	v_mfma_f32_16x16x32_bf16 v[6:9], v[10:13], v[122:125], 0
	v_mfma_f32_16x16x32_bf16 v[130:133], v[10:13], v[114:117], 0
	v_mfma_f32_16x16x32_bf16 v[6:9], v[14:17], v[126:129], v[6:9]
	v_mfma_f32_16x16x32_bf16 v[166:169], v[14:17], v[118:121], v[130:133]
	v_mfma_f32_16x16x32_bf16 v[10:13], v[18:21], v[62:65], 0
	v_mfma_f32_16x16x32_bf16 v[180:183], v[22:25], v[102:105], v[10:13]
	v_mfma_f32_16x16x32_bf16 v[10:13], v[26:29], v[62:65], 0
	v_mfma_f32_16x16x32_bf16 v[184:187], v[30:33], v[102:105], v[10:13]
	v_mfma_f32_16x16x32_bf16 v[10:13], v[18:21], v[106:109], 0
	v_mfma_f32_16x16x32_bf16 v[188:191], v[22:25], v[110:113], v[10:13]
	v_mfma_f32_16x16x32_bf16 v[10:13], v[26:29], v[106:109], 0
	v_mfma_f32_16x16x32_bf16 v[196:199], v[30:33], v[110:113], v[10:13]
	v_mfma_f32_16x16x32_bf16 v[10:13], v[18:21], v[114:117], 0
	v_mfma_f32_16x16x32_bf16 v[200:203], v[22:25], v[118:121], v[10:13]
	v_mfma_f32_16x16x32_bf16 v[10:13], v[26:29], v[114:117], 0
	v_mfma_f32_16x16x32_bf16 v[204:207], v[30:33], v[118:121], v[10:13]
	v_mfma_f32_16x16x32_bf16 v[10:13], v[18:21], v[122:125], 0
	v_mfma_f32_16x16x32_bf16 v[208:211], v[22:25], v[126:129], v[10:13]
	v_mfma_f32_16x16x32_bf16 v[10:13], v[26:29], v[122:125], 0
	v_mfma_f32_16x16x32_bf16 v[212:215], v[30:33], v[126:129], v[10:13]
	s_barrier
	s_nop 5
	ds_read_b128 v[10:13], v194
	ds_read_b128 v[14:17], v194 offset:1024
	ds_read_b128 v[18:21], v194 offset:2048
	ds_read_b128 v[22:25], v194 offset:3072
	ds_read_b128 v[216:219], v195
	ds_read_b128 v[220:223], v195 offset:1024
	ds_read_b128 v[224:227], v195 offset:2048
	ds_read_b128 v[228:231], v195 offset:3072
	s_mov_b32 m0, s53
	v_lshl_add_u64 v[106:107], v[248:249], 0, s[20:21]
	ds_read_b128 v[26:29], v193 offset:32768
	ds_read_b128 v[30:33], v193 offset:33792
	ds_read_b128 v[62:65], v193 offset:34816
	ds_read_b128 v[102:105], v193 offset:35840
	ds_read_b128 v[232:235], v193 offset:36864
	ds_read_b128 v[236:239], v193 offset:37888
	ds_read_b128 v[240:243], v193 offset:38912
	ds_read_b128 v[244:247], v193 offset:39936
	global_load_lds_dwordx4 v[106:107], off
	v_lshl_add_u64 v[106:107], v[248:249], 0, s[22:23]
	s_mov_b32 m0, s54
	s_nop 0
	global_load_lds_dwordx4 v[106:107], off
	s_waitcnt vmcnt(8)
	s_waitcnt lgkmcnt(0)
	s_barrier
	s_waitcnt lgkmcnt(0)
	v_mfma_f32_16x16x32_bf16 v[66:69], v[10:13], v[26:29], v[66:69]
	v_mfma_f32_16x16x32_bf16 v[146:149], v[14:17], v[30:33], v[66:69]
	v_mfma_f32_16x16x32_bf16 v[66:69], v[18:21], v[26:29], v[70:73]
	v_mfma_f32_16x16x32_bf16 v[142:145], v[22:25], v[30:33], v[66:69]
	v_mfma_f32_16x16x32_bf16 v[66:69], v[10:13], v[62:65], v[74:77]
	v_mfma_f32_16x16x32_bf16 v[126:129], v[14:17], v[102:105], v[66:69]
	v_mfma_f32_16x16x32_bf16 v[66:69], v[18:21], v[62:65], v[78:81]
	v_mfma_f32_16x16x32_bf16 v[122:125], v[22:25], v[102:105], v[66:69]
	v_mfma_f32_16x16x32_bf16 v[66:69], v[10:13], v[232:235], v[82:85]
	v_mfma_f32_16x16x32_bf16 v[110:113], v[14:17], v[236:239], v[66:69]
	v_mfma_f32_16x16x32_bf16 v[66:69], v[18:21], v[232:235], v[86:89]
	v_mfma_f32_16x16x32_bf16 v[106:109], v[22:25], v[236:239], v[66:69]
	v_mfma_f32_16x16x32_bf16 v[66:69], v[10:13], v[240:243], v[90:93]
	v_mfma_f32_16x16x32_bf16 v[86:89], v[14:17], v[244:247], v[66:69]
	v_mfma_f32_16x16x32_bf16 v[66:69], v[18:21], v[240:243], v[94:97]
	v_mfma_f32_16x16x32_bf16 v[78:81], v[22:25], v[244:247], v[66:69]
	v_mfma_f32_16x16x32_bf16 v[66:69], v[216:219], v[26:29], v[98:101]
	v_mfma_f32_16x16x32_bf16 v[26:29], v[224:227], v[26:29], v[34:37]
	v_mfma_f32_16x16x32_bf16 v[130:133], v[228:231], v[30:33], v[26:29]
	v_mfma_f32_16x16x32_bf16 v[26:29], v[216:219], v[62:65], v[38:41]
	v_mfma_f32_16x16x32_bf16 v[118:121], v[220:223], v[102:105], v[26:29]
	v_mfma_f32_16x16x32_bf16 v[26:29], v[224:227], v[62:65], v[42:45]
	v_mfma_f32_16x16x32_bf16 v[114:117], v[228:231], v[102:105], v[26:29]
	v_mfma_f32_16x16x32_bf16 v[26:29], v[216:219], v[232:235], v[46:49]
	v_mfma_f32_16x16x32_bf16 v[102:105], v[220:223], v[236:239], v[26:29]
	v_mfma_f32_16x16x32_bf16 v[26:29], v[224:227], v[232:235], v[50:53]
	v_mfma_f32_16x16x32_bf16 v[98:101], v[228:231], v[236:239], v[26:29]
	v_mfma_f32_16x16x32_bf16 v[26:29], v[216:219], v[240:243], v[54:57]
	v_mfma_f32_16x16x32_bf16 v[70:73], v[220:223], v[244:247], v[26:29]
	v_mfma_f32_16x16x32_bf16 v[26:29], v[224:227], v[240:243], v[58:61]
	v_mfma_f32_16x16x32_bf16 v[134:137], v[220:223], v[30:33], v[66:69]
	v_mfma_f32_16x16x32_bf16 v[66:69], v[228:231], v[244:247], v[26:29]
	s_barrier
	s_add_i32 s50, s88, s46
	s_nop 3
	v_lshl_add_u64 v[26:27], v[250:251], 0, s[24:25]
	s_mov_b32 m0, s50
	s_add_i32 s51, s50, 0x2000
	ds_read_b128 v[34:37], v193 offset:49152
	ds_read_b128 v[38:41], v193 offset:50176
	ds_read_b128 v[74:77], v193 offset:51200
	ds_read_b128 v[82:85], v193 offset:52224
	ds_read_b128 v[90:93], v193 offset:53248
	ds_read_b128 v[94:97], v193 offset:54272
	ds_read_b128 v[232:235], v193 offset:55296
	ds_read_b128 v[236:239], v193 offset:56320
	global_load_lds_dwordx4 v[26:27], off
	v_lshl_add_u64 v[26:27], v[250:251], 0, s[26:27]
	s_mov_b32 m0, s51
	s_mov_b64 s[0:1], 0x80180
	s_add_i32 s33, s89, s46
	global_load_lds_dwordx4 v[26:27], off
	v_lshl_add_u64 v[26:27], v[250:251], 0, s[0:1]
	s_mov_b32 m0, s33
	s_mov_b64 s[0:1], 0xc0180
	s_add_i32 s56, s33, 0x2000
	global_load_lds_dwordx4 v[26:27], off
	v_lshl_add_u64 v[26:27], v[250:251], 0, s[0:1]
	s_mov_b32 m0, s56
	s_nop 0
	global_load_lds_dwordx4 v[26:27], off
	v_lshl_add_u64 v[26:27], v[248:249], 0, s[24:25]
	s_mov_b32 m0, s55
	s_nop 0
	global_load_lds_dwordx4 v[26:27], off
	v_lshl_add_u64 v[26:27], v[248:249], 0, s[26:27]
	s_mov_b32 m0, s62
	s_nop 0
	global_load_lds_dwordx4 v[26:27], off
	s_waitcnt vmcnt(8)
	s_waitcnt lgkmcnt(0)
	s_barrier
	s_waitcnt lgkmcnt(0)
	v_mfma_f32_16x16x32_bf16 v[26:29], v[10:13], v[34:37], v[138:141]
	v_mfma_f32_16x16x32_bf16 v[62:65], v[14:17], v[38:41], v[26:29]
	v_mfma_f32_16x16x32_bf16 v[26:29], v[18:21], v[34:37], v[150:153]
	v_mfma_f32_16x16x32_bf16 v[58:61], v[22:25], v[38:41], v[26:29]
	v_mfma_f32_16x16x32_bf16 v[26:29], v[10:13], v[74:77], v[154:157]
	v_mfma_f32_16x16x32_bf16 v[46:49], v[14:17], v[82:85], v[26:29]
	v_mfma_f32_16x16x32_bf16 v[26:29], v[18:21], v[74:77], v[158:161]
	v_mfma_f32_16x16x32_bf16 v[42:45], v[22:25], v[82:85], v[26:29]
	v_mfma_f32_16x16x32_bf16 v[26:29], v[10:13], v[90:93], v[162:165]
	v_mfma_f32_16x16x32_bf16 v[2:5], v[10:13], v[232:235], v[2:5]
	v_mfma_f32_16x16x32_bf16 v[30:33], v[14:17], v[94:97], v[26:29]
	v_mfma_f32_16x16x32_bf16 v[26:29], v[18:21], v[90:93], v[166:169]
	v_mfma_f32_16x16x32_bf16 v[14:17], v[14:17], v[236:239], v[2:5]
	v_mfma_f32_16x16x32_bf16 v[2:5], v[18:21], v[232:235], v[6:9]
	v_mfma_f32_16x16x32_bf16 v[26:29], v[22:25], v[94:97], v[26:29]
	v_mfma_f32_16x16x32_bf16 v[10:13], v[22:25], v[236:239], v[2:5]
	v_mfma_f32_16x16x32_bf16 v[2:5], v[216:219], v[34:37], v[180:183]
	v_mfma_f32_16x16x32_bf16 v[54:57], v[220:223], v[38:41], v[2:5]
	v_mfma_f32_16x16x32_bf16 v[2:5], v[224:227], v[34:37], v[184:187]
	v_mfma_f32_16x16x32_bf16 v[50:53], v[228:231], v[38:41], v[2:5]
	v_mfma_f32_16x16x32_bf16 v[2:5], v[216:219], v[74:77], v[188:191]
	v_mfma_f32_16x16x32_bf16 v[38:41], v[220:223], v[82:85], v[2:5]
	v_mfma_f32_16x16x32_bf16 v[2:5], v[224:227], v[74:77], v[196:199]
	v_mfma_f32_16x16x32_bf16 v[34:37], v[228:231], v[82:85], v[2:5]
	v_mfma_f32_16x16x32_bf16 v[2:5], v[216:219], v[90:93], v[200:203]
	v_mfma_f32_16x16x32_bf16 v[22:25], v[220:223], v[94:97], v[2:5]
	v_mfma_f32_16x16x32_bf16 v[2:5], v[224:227], v[90:93], v[204:207]
	v_mfma_f32_16x16x32_bf16 v[18:21], v[228:231], v[94:97], v[2:5]
	v_mfma_f32_16x16x32_bf16 v[2:5], v[216:219], v[232:235], v[208:211]
	v_mfma_f32_16x16x32_bf16 v[6:9], v[220:223], v[236:239], v[2:5]
	v_mfma_f32_16x16x32_bf16 v[2:5], v[224:227], v[232:235], v[212:215]
	v_mfma_f32_16x16x32_bf16 v[2:5], v[228:231], v[236:239], v[2:5]
	s_barrier
	s_add_u32 s74, s74, 0x80180
	s_addc_u32 s75, s75, 0
	s_add_u32 s57, s76, 0x200
	s_addc_u32 s76, s77, 0
	s_mov_b32 s77, 0

; template <class Epi, class Sched, bool ALIGN_EPI = true, bool SP2 = true, bool FULLLINE = false, bool NOSTAGE = false, bool FP8 = false>
; __device__ __forceinline__ void gemm_phase(PG8_LAS unsigned char* lds, const Gemm g, const Sched& S, const Epi& E) {
;     ...
;     for (;;) {
;         const bool has_next = S.next(ui + 1, nxt);
;         const char* nA = has_next ? PG8_ABASE(nxt) : cA; const char* nB = has_next ? PG8_BBASE(nxt) : cB;
.LBB0_2385:
	s_lshl_b32 s100, s81, 20
	s_lshl_b32 s101, s82, 9
	s_add_u32 s100, s100, s101
	s_add_u32 s100, s60, s100
	s_addc_u32 s101, s61, 0
	v_lshrrev_b32_e32 v253, 2, v0
	v_and_b32_e32 v254, 3, v0
	v_lshlrev_b32_e32 v253, 12, v253
	v_lshl_or_b32 v253, v254, 7, v253
	s_nop 0
	global_load_dword v254, v253, s[100:101]
	s_add_u32 s100, s100, 0x80000
	s_addc_u32 s101, s101, 0
	s_nop 0
	global_load_dword v254, v253, s[100:101]
	s_nop 0
	v_cndmask_b32_e64 v2, 0, 1, s[10:11]
	v_cmp_ne_u32_e64 s[8:9], 1, v2
	s_andn2_b64 vcc, exec, s[10:11]
	s_mov_b64 s[10:11], s[66:67]
	s_cbranch_vccnz .LBB0_2387
	s_mul_i32 s1, s80, 0x2c0000
	s_mul_hi_i32 s0, s80, 0x2c0000
	s_add_u32 s10, s96, s1
	s_addc_u32 s11, s97, s0

; template <class Epi, class Sched, bool ALIGN_EPI = true, bool SP2 = true, bool FULLLINE = false, bool NOSTAGE = false, bool FP8 = false>
; __device__ __forceinline__ void gemm_phase(PG8_LAS unsigned char* lds, const Gemm g, const Sched& S, const Epi& E) {
;     ...
;     for (;;) {
;         const bool has_next = S.next(ui + 1, nxt);
;         const char* nA = has_next ? PG8_ABASE(nxt) : cA; const char* nB = has_next ? PG8_BBASE(nxt) : cB;
.LBB0_2960:
	s_lshl_b32 s100, s79, 20
	s_lshl_b32 s101, s80, 9
	s_add_u32 s100, s100, s101
	s_add_u32 s100, s60, s100
	s_addc_u32 s101, s61, 0
	v_lshrrev_b32_e32 v253, 2, v0
	v_and_b32_e32 v254, 3, v0
	v_lshlrev_b32_e32 v253, 12, v253
	v_lshl_or_b32 v253, v254, 7, v253
	s_nop 0
	global_load_dword v254, v253, s[100:101]
	s_add_u32 s100, s100, 0x80000
	s_addc_u32 s101, s101, 0
	s_nop 0
	global_load_dword v254, v253, s[100:101]
	s_nop 0
	v_cndmask_b32_e64 v2, 0, 1, s[10:11]
	v_cmp_ne_u32_e64 s[8:9], 1, v2
	s_andn2_b64 vcc, exec, s[10:11]
	s_mov_b64 s[10:11], s[46:47]
	s_cbranch_vccnz .LBB0_2962
	s_mul_i32 s1, s78, 0x2c0000
	s_mul_hi_i32 s0, s78, 0x2c0000
	s_add_u32 s10, s96, s1
	s_addc_u32 s11, s97, s0
